# v26 + SWA unit prologue: the 3-4 iterations of the resident K/V window staging loop issue all their loads first (VGPRs untouched by the SWA phase), then drain in order with exact vmcnt (was one memory
# speedup vs baseline: 1.0000x; 1.0000x over previous
; #define LAS __attribute__((address_space(3)))
; __device__ __forceinline__ int fresh_tid(int wave_s) { return wave_s * 64 + lane_id(); }
; __global__ void __launch_bounds__(512) fwd_megakernel(Args a) {
;     ...
;                 { const int t2 = fresh_tid(wave_s); const int key = t2 >> 3, c = t2 & 7;
;                   const bf16_t* kp = ACT + (tok0 + 64 * klo + key) * INP + C_KB + 64 * kvh + 8 * c; const bf16_t* vp = ACT + (tok0 + 64 * klo + key) * INP + C_VB + 64 * kvh + 8 * c;
;                   LAS unsigned char* kd = lds + key * 144 + 16 * c; LAS unsigned char* vd = lds + 8 * SW_KBUF + (c >> 2) * 4096 + (key >> 3) * 512 + (key & 7) * 64 + (c & 3) * 16;
;                   for (int i = 0; i < khi - klo; i += 2) {
;                       const u32x4 k0 = *(const u32x4*)(kp + (size_t)(64 * i) * INP), v0 = *(const u32x4*)(vp + (size_t)(64 * i) * INP);
;                       const u32x4 k1 = *(const u32x4*)(kp + (size_t)(64 * (i + 1)) * INP), v1 = *(const u32x4*)(vp + (size_t)(64 * (i + 1)) * INP);
;                       *(LAS u32x4*)(kd + i * SW_KBUF) = k0; *(LAS u32x4*)(vd + i * SW_VBUF) = v0; *(LAS u32x4*)(kd + (i + 1) * SW_KBUF) = k1; *(LAS u32x4*)(vd + (i + 1) * SW_VBUF) = v1; } }
.LBB0_811:
	s_add_i32 s7, s1, 1
	s_lshr_b32 s7, s7, 1
	global_load_dwordx4 v[6:9], v[2:3], off
	global_load_dwordx4 v[10:13], v[2:3], off offset:512
	v_add_co_u32_e32 v18, vcc, 0x108000, v2
	s_nop 1
	v_addc_co_u32_e32 v19, vcc, 0, v3, vcc
	global_load_dwordx4 v[14:17], v[18:19], off
	global_load_dwordx4 v[18:21], v[18:19], off offset:512
	v_lshl_add_u64 v[2:3], v[2:3], 0, s[54:55]
	s_cmp_lt_u32 s7, 2
	s_cbranch_scc1 .Lswa_d1
	global_load_dwordx4 v[222:225], v[2:3], off
	global_load_dwordx4 v[226:229], v[2:3], off offset:512
	v_add_co_u32_e32 v234, vcc, 0x108000, v2
	s_nop 1
	v_addc_co_u32_e32 v235, vcc, 0, v3, vcc
	global_load_dwordx4 v[230:233], v[234:235], off
	global_load_dwordx4 v[234:237], v[234:235], off offset:512
	v_lshl_add_u64 v[2:3], v[2:3], 0, s[54:55]
	s_cmp_lt_u32 s7, 3
	s_cbranch_scc1 .Lswa_d2
	global_load_dwordx4 v[242:245], v[2:3], off
	global_load_dwordx4 v[246:249], v[2:3], off offset:512
	v_add_co_u32_e32 v170, vcc, 0x108000, v2
	s_nop 1
	v_addc_co_u32_e32 v171, vcc, 0, v3, vcc
	global_load_dwordx4 v[166:169], v[170:171], off
	global_load_dwordx4 v[170:173], v[170:171], off offset:512
	v_lshl_add_u64 v[2:3], v[2:3], 0, s[54:55]
	s_cmp_lt_u32 s7, 4
	s_cbranch_scc1 .Lswa_d3
	global_load_dwordx4 v[174:177], v[2:3], off
	global_load_dwordx4 v[192:195], v[2:3], off offset:512
	v_add_co_u32_e32 v218, vcc, 0x108000, v2
	s_nop 1
	v_addc_co_u32_e32 v219, vcc, 0, v3, vcc
	global_load_dwordx4 v[196:199], v[218:219], off
	global_load_dwordx4 v[218:221], v[218:219], off offset:512
	v_lshl_add_u64 v[2:3], v[2:3], 0, s[54:55]
	v_add_u32_e32 v5, 0xffffe000, v4
	s_waitcnt vmcnt(15)
	ds_write_b128 v0, v[6:9]
	s_waitcnt vmcnt(14)
	ds_write_b128 v5, v[10:13]
	s_waitcnt vmcnt(13)
	ds_write_b128 v0, v[14:17] offset:9216
	s_waitcnt vmcnt(12)
	ds_write_b128 v4, v[18:21]
	v_add_u32_e32 v0, 0x4800, v0
	v_add_u32_e32 v4, 0x4000, v4
	v_add_u32_e32 v5, 0xffffe000, v4
	s_waitcnt vmcnt(11)
	ds_write_b128 v0, v[222:225]
	s_waitcnt vmcnt(10)
	ds_write_b128 v5, v[226:229]
	s_waitcnt vmcnt(9)
	ds_write_b128 v0, v[230:233] offset:9216
	s_waitcnt vmcnt(8)
	ds_write_b128 v4, v[234:237]
	v_add_u32_e32 v0, 0x4800, v0
	v_add_u32_e32 v4, 0x4000, v4
	v_add_u32_e32 v5, 0xffffe000, v4
	s_waitcnt vmcnt(7)
	ds_write_b128 v0, v[242:245]
	s_waitcnt vmcnt(6)
	ds_write_b128 v5, v[246:249]
	s_waitcnt vmcnt(5)
	ds_write_b128 v0, v[166:169] offset:9216
	s_waitcnt vmcnt(4)
	ds_write_b128 v4, v[170:173]
	v_add_u32_e32 v0, 0x4800, v0
	v_add_u32_e32 v4, 0x4000, v4
	v_add_u32_e32 v5, 0xffffe000, v4
	s_waitcnt vmcnt(3)
	ds_write_b128 v0, v[174:177]
	s_waitcnt vmcnt(2)
	ds_write_b128 v5, v[192:195]
	s_waitcnt vmcnt(1)
	ds_write_b128 v0, v[196:199] offset:9216
	s_waitcnt vmcnt(0)
	ds_write_b128 v4, v[218:221]
	v_add_u32_e32 v0, 0x4800, v0
	v_add_u32_e32 v4, 0x4000, v4
	s_branch .Lswa_done
.Lswa_d3:
	v_add_u32_e32 v5, 0xffffe000, v4
	s_waitcnt vmcnt(11)
	ds_write_b128 v0, v[6:9]
	s_waitcnt vmcnt(10)
	ds_write_b128 v5, v[10:13]
	s_waitcnt vmcnt(9)
	ds_write_b128 v0, v[14:17] offset:9216
	s_waitcnt vmcnt(8)
	ds_write_b128 v4, v[18:21]
	v_add_u32_e32 v0, 0x4800, v0
	v_add_u32_e32 v4, 0x4000, v4
	v_add_u32_e32 v5, 0xffffe000, v4
	s_waitcnt vmcnt(7)
	ds_write_b128 v0, v[222:225]
	s_waitcnt vmcnt(6)
	ds_write_b128 v5, v[226:229]
	s_waitcnt vmcnt(5)
	ds_write_b128 v0, v[230:233] offset:9216
	s_waitcnt vmcnt(4)
	ds_write_b128 v4, v[234:237]
	v_add_u32_e32 v0, 0x4800, v0
	v_add_u32_e32 v4, 0x4000, v4
	v_add_u32_e32 v5, 0xffffe000, v4
	s_waitcnt vmcnt(3)
	ds_write_b128 v0, v[242:245]
	s_waitcnt vmcnt(2)
	ds_write_b128 v5, v[246:249]
	s_waitcnt vmcnt(1)
	ds_write_b128 v0, v[166:169] offset:9216
	s_waitcnt vmcnt(0)
	ds_write_b128 v4, v[170:173]
	v_add_u32_e32 v0, 0x4800, v0
	v_add_u32_e32 v4, 0x4000, v4
	s_branch .Lswa_done
.Lswa_d2:
	v_add_u32_e32 v5, 0xffffe000, v4
	s_waitcnt vmcnt(7)
	ds_write_b128 v0, v[6:9]
	s_waitcnt vmcnt(6)
	ds_write_b128 v5, v[10:13]
	s_waitcnt vmcnt(5)
	ds_write_b128 v0, v[14:17] offset:9216
	s_waitcnt vmcnt(4)
	ds_write_b128 v4, v[18:21]
	v_add_u32_e32 v0, 0x4800, v0
	v_add_u32_e32 v4, 0x4000, v4
	v_add_u32_e32 v5, 0xffffe000, v4
	s_waitcnt vmcnt(3)
	ds_write_b128 v0, v[222:225]
	s_waitcnt vmcnt(2)
	ds_write_b128 v5, v[226:229]
	s_waitcnt vmcnt(1)
	ds_write_b128 v0, v[230:233] offset:9216
	s_waitcnt vmcnt(0)
	ds_write_b128 v4, v[234:237]
	v_add_u32_e32 v0, 0x4800, v0
	v_add_u32_e32 v4, 0x4000, v4
	s_branch .Lswa_done
.Lswa_d1:
	v_add_u32_e32 v5, 0xffffe000, v4
	s_waitcnt vmcnt(3)
	ds_write_b128 v0, v[6:9]
	s_waitcnt vmcnt(2)
	ds_write_b128 v5, v[10:13]
	s_waitcnt vmcnt(1)
	ds_write_b128 v0, v[14:17] offset:9216
	s_waitcnt vmcnt(0)
	ds_write_b128 v4, v[18:21]
	v_add_u32_e32 v0, 0x4800, v0
	v_add_u32_e32 v4, 0x4000, v4
.Lswa_done:
	s_lshl_b32 s7, s7, 1
	s_cmp_ge_i32 s7, s1
